# v27 plus attention loop: visibility test rewritten as k < tpos - spos0 (one subtract per key block instead of one v_or per element)
# baseline (speedup 1.0000x reference)
; #define LAS __attribute__((address_space(3)))
; #define MFMA16(a, b, c) __builtin_amdgcn_mfma_f32_16x16x32_bf16((a), (b), (c), 0, 0, 0)
; __device__ __forceinline__ void attn_phase(Frame& F, bf16* OZ) {
;     ...
;             const int spos0 = !smp ? (2 * qb + 1 - kb) * 64 : (kb == 0 ? 1024 : 1024 - 64 * kb), nvalid = (smp && kb == 0) ? 16 : 64;
;             if (kb > 0) { ATT_LOAD_KV(kb); __syncthreads(); }
;             bool done = true;
;             const bool none_visible = spos0 > __builtin_amdgcn_readfirstlane(tpos - l15) + 14;
;             if (active && none_visible) done = false;
;             if (active && !none_visible) {
;                 f32x4 sc[4];
; #pragma unroll
;                 for (int sb = 0; sb < 4; ++sb) { sc[sb] = (f32x4){0.f, 0.f, 0.f, 0.f};
; #pragma unroll
;                     for (int ks = 0; ks < 4; ++ks) { const bf16x8 a = *(const LAS bf16x8*)(L + KS + (16 * sb + l15) * ST_ + (32 * ks + 8 * g4) * 2); sc[sb] = MFMA16(a, qf[ks], sc[sb]); } }
;                 float lk[4][4], tsum[4], above[4], ttot[4];
; #pragma unroll
;                 for (int sb = 0; sb < 4; ++sb) { tsum[sb] = 0.f;
; #pragma unroll
;                     for (int e = 0; e < 4; ++e) { const int s = 16 * sb + 4 * g4 + e; const float z = sc[sb][e]; const bool vis = (s < nvalid) && (spos0 + s < tpos);
;                         const float sp = fmaxf(z, 0.f) + __logf(1.0f + __expf(-fabsf(z)));
;                         lk[sb][e] = vis ? -sp : 0.f; sc[sb][e] = vis ? z - sp : -1e30f; tsum[sb] += lk[sb][e]; }
;                     const float v1 = __shfl_xor(tsum[sb], 16), v2 = __shfl_xor(tsum[sb], 32), v3 = __shfl_xor(tsum[sb], 48);
.LBB0_1910:
	s_add_i32 s1, s60, s21
	s_and_b64 s[18:19], s[38:39], exec
	s_cselect_b32 s18, s0, s1
	v_readfirstlane_b32 s0, v150
	s_add_i32 s0, s0, 14
	s_cmp_gt_i32 s18, s0
	s_cselect_b64 s[0:1], -1, 0
	s_andn2_b64 s[0:1], s[0:1], s[64:65]
	s_or_b64 s[24:25], s[42:43], s[0:1]
	s_or_b64 s[24:25], s[24:25], s[64:65]
	s_and_b64 vcc, exec, s[24:25]
	s_waitcnt vmcnt(3)
	ds_write_b128 v144, v[58:61] offset:34816
	s_waitcnt vmcnt(2)
	ds_write_b128 v144, v[62:65] offset:52224
	s_waitcnt vmcnt(1)
	ds_write_b128 v145, v[66:69] offset:34816
	s_waitcnt vmcnt(0)
	ds_write_b128 v145, v[70:73] offset:52224
	s_waitcnt lgkmcnt(0)
	s_barrier
	s_cbranch_vccnz .LBB0_1912
	v_subrev_u32_e32 v238, s18, v90
	ds_read_b128 v[58:61], v146 offset:34816
	ds_read_b128 v[62:65], v146 offset:34880
	ds_read_b128 v[66:69], v146 offset:39168
	ds_read_b128 v[70:73], v146 offset:39232
	ds_read_b128 v[94:97], v146 offset:34944
	v_and_b32_e32 v5, 64, v147
	s_waitcnt lgkmcnt(4)
	v_mfma_f32_16x16x32_bf16 v[58:61], v[58:61], v[10:13], 0
	v_xor_b32_e32 v4, 16, v147
	v_add_u32_e32 v5, 64, v5
	v_cmp_lt_i32_e32 vcc, v4, v5
	s_waitcnt lgkmcnt(3)
	v_mfma_f32_16x16x32_bf16 v[58:61], v[62:65], v[14:17], v[58:61]
	ds_read_b128 v[62:65], v146 offset:35008
	ds_read_b128 v[154:157], v146 offset:39296
	ds_read_b128 v[158:161], v146 offset:39360
	v_cndmask_b32_e32 v4, v147, v4, vcc
	s_waitcnt lgkmcnt(5)
	v_mfma_f32_16x16x32_bf16 v[66:69], v[66:69], v[10:13], 0
	s_waitcnt lgkmcnt(3)
	v_mfma_f32_16x16x32_bf16 v[58:61], v[94:97], v[18:21], v[58:61]
	ds_read_b128 v[94:97], v146 offset:43520
	ds_read_b128 v[162:165], v146 offset:43584
	ds_read_b128 v[166:169], v146 offset:43648
	ds_read_b128 v[170:173], v146 offset:43712
	ds_read_b128 v[174:177], v146 offset:47872
	ds_read_b128 v[178:181], v146 offset:47936
	ds_read_b128 v[184:187], v146 offset:48000
	ds_read_b128 v[188:191], v146 offset:48064
	s_waitcnt lgkmcnt(10)
	v_mfma_f32_16x16x32_bf16 v[62:65], v[62:65], v[22:25], v[58:61]
	v_mfma_f32_16x16x32_bf16 v[58:61], v[70:73], v[14:17], v[66:69]
	s_waitcnt lgkmcnt(9)
	v_mfma_f32_16x16x32_bf16 v[58:61], v[154:157], v[18:21], v[58:61]
	v_lshlrev_b32_e32 v156, 2, v4
	v_xor_b32_e32 v4, 32, v147
	v_cmp_lt_i32_e32 vcc, v4, v5
	s_waitcnt lgkmcnt(8)
	v_mfma_f32_16x16x32_bf16 v[58:61], v[158:161], v[22:25], v[58:61]
	v_cndmask_b32_e32 v4, v147, v4, vcc
	v_lshlrev_b32_e32 v154, 2, v4
	v_xor_b32_e32 v4, 48, v147
	v_cmp_lt_i32_e32 vcc, v4, v5
	s_waitcnt lgkmcnt(7)
	v_mfma_f32_16x16x32_bf16 v[66:69], v[94:97], v[10:13], 0
	v_cndmask_b32_e32 v4, v147, v4, vcc
	v_lshlrev_b32_e32 v155, 2, v4
	v_mul_f32_e64 v4, |v62|, s49
	v_exp_f32_e32 v4, v4
	s_waitcnt lgkmcnt(6)
	v_mfma_f32_16x16x32_bf16 v[66:69], v[162:165], v[14:17], v[66:69]
	v_add_f32_e32 v4, 1.0, v4
	s_waitcnt lgkmcnt(5)
	v_mfma_f32_16x16x32_bf16 v[66:69], v[166:169], v[18:21], v[66:69]
	v_log_f32_e32 v4, v4
	v_max_f32_e32 v5, 0, v62
	s_waitcnt lgkmcnt(4)
	v_mfma_f32_16x16x32_bf16 v[70:73], v[170:173], v[22:25], v[66:69]
	v_mul_f32_e32 v92, 0x3f317217, v4
	v_fma_f32 v92, v4, s53, -v92
	v_fmac_f32_e32 v92, 0x3377d1cf, v4
	v_fma_f32 v4, v4, s53, v92
	s_waitcnt lgkmcnt(3)
	v_mfma_f32_16x16x32_bf16 v[66:69], v[174:177], v[10:13], 0
	v_mul_f32_e64 v92, |v63|, s49
	v_exp_f32_e32 v92, v92
	v_add_f32_e32 v4, v5, v4
	v_sub_f32_e32 v161, v62, v4
	v_sub_f32_e32 v160, 0, v4
	v_add_f32_e32 v4, 1.0, v92
	v_max_f32_e32 v62, 0, v63
	v_log_f32_e32 v4, v4
	s_waitcnt lgkmcnt(2)
	v_mfma_f32_16x16x32_bf16 v[66:69], v[178:181], v[14:17], v[66:69]
	v_mul_f32_e32 v92, 0x3f317217, v4
	v_fma_f32 v92, v4, s53, -v92
	v_fmac_f32_e32 v92, 0x3377d1cf, v4
	v_fma_f32 v4, v4, s53, v92
	s_waitcnt lgkmcnt(1)
	v_mfma_f32_16x16x32_bf16 v[66:69], v[184:187], v[18:21], v[66:69]
	v_cmp_gt_i32_e32 vcc, v238, v98
	v_mul_f32_e64 v5, |v64|, s49
	v_exp_f32_e32 v5, v5
	v_add_f32_e32 v62, v62, v4
	v_cndmask_b32_e64 v4, 0, -v62, vcc
	v_sub_f32_e32 v62, v63, v62
	v_add_f32_e32 v5, 1.0, v5
	v_cndmask_b32_e32 v157, v149, v62, vcc
	v_mul_f32_e64 v92, |v65|, s49
	v_exp_f32_e32 v92, v92
	v_log_f32_e32 v5, v5
	v_max_f32_e32 v94, 0, v64
	s_waitcnt lgkmcnt(0)
	v_mfma_f32_16x16x32_bf16 v[66:69], v[188:191], v[22:25], v[66:69]
	v_mul_f32_e32 v62, 0x3f317217, v5
	v_fma_f32 v62, v5, s53, -v62
	v_fmac_f32_e32 v62, 0x3377d1cf, v5
	v_fma_f32 v5, v5, s53, v62
	s_nop 0
	v_mov_b32_e32 v96, v5
	v_add_f32_e32 v5, 1.0, v92
	v_max_f32_e32 v92, 0, v65
	v_log_f32_e32 v5, v5
	s_nop 0
	v_mul_f32_e32 v95, 0x3f317217, v5
	v_fma_f32 v95, v5, s53, -v95
	v_fmac_f32_e32 v95, 0x3377d1cf, v5
	v_fma_f32 v5, v5, s53, v95
	s_nop 1
	v_add_f32_e32 v5, v92, v5
	v_mul_f32_e64 v92, |v58|, s49
	v_exp_f32_e32 v92, v92
	v_cmp_gt_i32_e32 vcc, v238, v99
	v_max_f32_e32 v95, 0, v58
	s_nop 0
	v_cndmask_b32_e64 v62, 0, -v5, vcc
	v_sub_f32_e32 v5, v65, v5
	v_cndmask_b32_e32 v65, v149, v5, vcc
	v_add_f32_e32 v5, 1.0, v92
	s_nop 1
	v_log_f32_e32 v5, v5
	s_nop 0
	v_mul_f32_e32 v97, 0x3f317217, v5
	v_fma_f32 v97, v5, s53, -v97
	v_fmac_f32_e32 v97, 0x3377d1cf, v5
	v_fma_f32 v5, v5, s53, v97
	s_nop 1
	v_add_f32_e32 v5, v95, v5
	v_mul_f32_e64 v95, |v59|, s49
	v_exp_f32_e32 v95, v95
	v_sub_f32_e32 v58, v58, v5
	v_cmp_gt_i32_e32 vcc, v238, v100
	v_sub_f32_e32 v5, 0, v5
	s_nop 0
	v_cndmask_b32_e32 v163, v149, v58, vcc
	v_add_f32_e32 v58, 1.0, v95
	v_cndmask_b32_e32 v5, 0, v5, vcc
	v_max_f32_e32 v95, 0, v59
	v_log_f32_e32 v58, v58
	s_nop 0
	v_mul_f32_e32 v97, 0x3f317217, v58
	v_fma_f32 v97, v58, s53, -v97
	v_fmac_f32_e32 v97, 0x3377d1cf, v58
	v_fma_f32 v58, v58, s53, v97
	s_nop 1
	v_add_f32_e32 v58, v95, v58
	v_mul_f32_e64 v95, |v60|, s49
	v_exp_f32_e32 v95, v95
	v_cmp_gt_i32_e32 vcc, v238, v101
	s_nop 1
	v_cndmask_b32_e64 v166, 0, -v58, vcc
	v_sub_f32_e32 v58, v59, v58
; __device__ __forceinline__ void attn_phase(Frame& F, bf16* OZ) {
;     ...
;                 for (int sb = 0; sb < 4; ++sb) { tsum[sb] = 0.f;
; #pragma unroll
;                     for (int e = 0; e < 4; ++e) { const int s = 16 * sb + 4 * g4 + e; const float z = sc[sb][e]; const bool vis = (s < nvalid) && (spos0 + s < tpos);
;                         const float sp = fmaxf(z, 0.f) + __logf(1.0f + __expf(-fabsf(z)));
;                         lk[sb][e] = vis ? -sp : 0.f; sc[sb][e] = vis ? z - sp : -1e30f; tsum[sb] += lk[sb][e]; }
;                     const float v1 = __shfl_xor(tsum[sb], 16), v2 = __shfl_xor(tsum[sb], 32), v3 = __shfl_xor(tsum[sb], 48);
;                     above[sb] = ((g4 ^ 1) > g4 ? v1 : 0.f) + ((g4 ^ 2) > g4 ? v2 : 0.f) + ((g4 ^ 3) > g4 ? v3 : 0.f);
;                     ttot[sb] = (tsum[sb] + v1) + (v2 + v3); }
	v_cndmask_b32_e32 v167, v149, v58, vcc
	v_add_f32_e32 v58, 1.0, v95
	v_cmp_gt_f32_e32 vcc, s52, v58
	v_add_f32_e32 v5, v166, v5
	s_nop 0
	v_cndmask_b32_e64 v59, 0, 32, vcc
	v_ldexp_f32 v58, v58, v59
	v_log_f32_e32 v58, v58
	v_cndmask_b32_e32 v95, 0, v148, vcc
	v_max_f32_e32 v59, 0, v60
	v_mul_f32_e32 v92, 0x3f317217, v58
	v_fma_f32 v92, v58, s53, -v92
	v_fmac_f32_e32 v92, 0x3377d1cf, v58
	v_fmac_f32_e32 v92, 0x3f317217, v58
	v_cmp_lt_f32_e64 s[0:1], |v58|, s54
	s_nop 1
	v_cndmask_b32_e64 v58, v58, v92, s[0:1]
	v_mul_f32_e64 v92, |v61|, s49
	v_exp_f32_e32 v92, v92
	v_sub_f32_e32 v58, v58, v95
	v_add_f32_e32 v165, v59, v58
	v_sub_f32_e32 v168, v60, v165
	v_add_f32_e32 v58, 1.0, v92
	v_mul_f32_e64 v60, |v70|, s49
	v_exp_f32_e32 v60, v60
	v_log_f32_e32 v58, v58
	v_max_f32_e32 v95, 0, v61
	v_mul_f32_e32 v59, 0x3f317217, v58
	v_fma_f32 v59, v58, s53, -v59
	v_fmac_f32_e32 v59, 0x3377d1cf, v58
	v_fma_f32 v58, v58, s53, v59
	s_nop 1
	v_mov_b32_e32 v97, v58
	v_add_f32_e32 v58, 1.0, v60
	v_max_f32_e32 v60, 0, v70
	v_log_f32_e32 v58, v58
	s_nop 0
	v_mul_f32_e32 v92, 0x3f317217, v58
	v_fma_f32 v92, v58, s53, -v92
	v_fmac_f32_e32 v92, 0x3377d1cf, v58
	v_fma_f32 v58, v58, s53, v92
	s_nop 1
	v_add_f32_e32 v58, v60, v58
	v_sub_f32_e32 v60, v70, v58
	v_mul_f32_e64 v70, |v71|, s49
	v_exp_f32_e32 v70, v70
	v_cmp_gt_i32_e32 vcc, v238, v102
	v_sub_f32_e32 v58, 0, v58
	v_add_f32_e32 v59, 1.0, v70
	v_cndmask_b32_e32 v169, v149, v60, vcc
	v_cndmask_b32_e32 v58, 0, v58, vcc
	v_max_f32_e32 v70, 0, v71
	v_log_f32_e32 v59, v59
	s_nop 0
	v_mul_f32_e32 v92, 0x3f317217, v59
	v_fma_f32 v92, v59, s53, -v92
	v_fmac_f32_e32 v92, 0x3377d1cf, v59
	v_fma_f32 v59, v59, s53, v92
	s_nop 1
	v_cmp_gt_i32_e32 vcc, v238, v103
	v_mul_f32_e64 v60, |v72|, s49
	v_exp_f32_e32 v60, v60
	v_add_f32_e32 v59, v70, v59
	v_cndmask_b32_e64 v170, 0, -v59, vcc
	v_sub_f32_e32 v59, v71, v59
	v_cndmask_b32_e32 v171, v149, v59, vcc
	v_add_f32_e32 v59, 1.0, v60
	v_max_f32_e32 v70, 0, v72
	v_log_f32_e32 v59, v59
	v_add_f32_e32 v58, v170, v58
	v_mul_f32_e32 v71, 0x3f317217, v59
	v_fma_f32 v71, v59, s53, -v71
	v_fmac_f32_e32 v71, 0x3377d1cf, v59
	v_fma_f32 v59, v59, s53, v71
	s_nop 1
	v_cmp_gt_i32_e32 vcc, v238, v104
	v_mul_f32_e64 v60, |v73|, s49
	v_exp_f32_e32 v60, v60
	v_add_f32_e32 v59, v70, v59
	v_cndmask_b32_e64 v172, 0, -v59, vcc
	v_sub_f32_e32 v59, v72, v59
	v_cndmask_b32_e32 v173, v149, v59, vcc
	v_add_f32_e32 v59, 1.0, v60
	v_max_f32_e32 v70, 0, v73
	v_log_f32_e32 v59, v59
	v_add_f32_e32 v58, v172, v58
	v_mul_f32_e32 v71, 0x3f317217, v59
	v_fma_f32 v71, v59, s53, -v71
	v_fmac_f32_e32 v71, 0x3377d1cf, v59
	v_fma_f32 v59, v59, s53, v71
	s_nop 1
	v_add_f32_e32 v71, v70, v59
	v_cmp_gt_i32_e32 vcc, v238, v105
	v_sub_f32_e32 v60, v73, v71
	s_nop 0
	v_cndmask_b32_e64 v174, 0, -v71, vcc
	v_add_f32_e32 v58, v174, v58
	ds_bpermute_b32 v59, v154, v58
	ds_bpermute_b32 v70, v156, v58
	ds_bpermute_b32 v71, v155, v58
	v_cndmask_b32_e32 v175, v149, v60, vcc
	v_mul_f32_e64 v60, |v66|, s49
	v_exp_f32_e32 v60, v60
	s_waitcnt lgkmcnt(2)
	v_cndmask_b32_e64 v72, 0, v59, s[6:7]
	s_waitcnt lgkmcnt(0)
	v_pk_add_f32 v[58:59], v[58:59], v[70:71]
	v_cndmask_b32_e64 v92, 0, v71, s[8:9]
	v_pk_add_f32 v[58:59], v[58:59], v[58:59] op_sel_hi:[0,1]
	v_add_f32_e32 v58, 1.0, v60
	v_cndmask_b32_e64 v164, 0, v70, s[4:5]
	v_log_f32_e32 v58, v58
	v_max_f32_e32 v70, 0, v66
	v_mul_f32_e32 v71, 0x3f317217, v58
	v_fma_f32 v71, v58, s53, -v71
	v_fmac_f32_e32 v71, 0x3377d1cf, v58
	v_fma_f32 v58, v58, s53, v71
	s_nop 1
	v_add_f32_e32 v58, v70, v58
	v_mul_f32_e64 v70, |v67|, s49
	v_exp_f32_e32 v70, v70
	v_sub_f32_e32 v66, v66, v58
	v_cmp_gt_i32_e32 vcc, v238, v106
	v_sub_f32_e32 v58, 0, v58
	v_add_f32_e32 v60, 1.0, v70
	v_cndmask_b32_e32 v176, v149, v66, vcc
	v_cndmask_b32_e32 v58, 0, v58, vcc
	v_max_f32_e32 v70, 0, v67
	v_log_f32_e32 v60, v60
	s_nop 0
	v_mul_f32_e32 v71, 0x3f317217, v60
	v_fma_f32 v71, v60, s53, -v71
	v_fmac_f32_e32 v71, 0x3377d1cf, v60
	v_fma_f32 v60, v60, s53, v71
	s_nop 1
	v_cmp_gt_i32_e32 vcc, v238, v107
	v_mul_f32_e64 v66, |v68|, s49
	v_exp_f32_e32 v66, v66
	v_add_f32_e32 v60, v70, v60
	v_cndmask_b32_e64 v177, 0, -v60, vcc
	v_sub_f32_e32 v60, v67, v60
	v_add_f32_e32 v66, 1.0, v66
	v_cndmask_b32_e32 v60, v149, v60, vcc
	v_max_f32_e32 v70, 0, v68
	v_log_f32_e32 v66, v66
	v_add_f32_e32 v58, v177, v58
	v_mul_f32_e32 v71, 0x3f317217, v66
	v_fma_f32 v71, v66, s53, -v71
	v_fmac_f32_e32 v71, 0x3377d1cf, v66
	v_fma_f32 v66, v66, s53, v71
	s_nop 1
	v_cmp_gt_i32_e32 vcc, v238, v108
	v_mul_f32_e64 v67, |v69|, s49
	v_exp_f32_e32 v67, v67
	v_add_f32_e32 v66, v70, v66
	v_cndmask_b32_e64 v70, 0, -v66, vcc
	v_sub_f32_e32 v66, v68, v66
	v_cndmask_b32_e32 v71, v149, v66, vcc
	v_add_f32_e32 v66, 1.0, v67
	v_max_f32_e32 v68, 0, v69
	v_log_f32_e32 v66, v66
	v_add_f32_e32 v58, v70, v58
	v_cmp_gt_i32_e64 s[18:19], v238, v1
	v_mul_f32_e32 v73, 0x3f317217, v66
	v_fma_f32 v73, v66, s53, -v73
	v_fmac_f32_e32 v73, 0x3377d1cf, v66
	v_fma_f32 v66, v66, s53, v73
	s_nop 1
	v_add_f32_e32 v73, v68, v66
	v_cmp_gt_i32_e32 vcc, v238, v109
	v_cmp_gt_i32_e64 s[0:1], v238, v88
	s_nop 0
	v_cndmask_b32_e64 v178, 0, -v73, vcc
	v_add_f32_e32 v66, v178, v58
	ds_bpermute_b32 v67, v154, v66
	ds_bpermute_b32 v68, v156, v66
	v_sub_f32_e32 v58, v69, v73
	ds_bpermute_b32 v69, v155, v66
	v_cndmask_b32_e32 v58, v149, v58, vcc
	s_waitcnt lgkmcnt(2)
	v_cndmask_b32_e64 v73, 0, v67, s[6:7]
	s_waitcnt lgkmcnt(1)
	v_cndmask_b32_e64 v179, 0, v68, s[4:5]
	v_add_f32_e32 v73, v179, v73
	s_waitcnt lgkmcnt(0)
; __device__ __forceinline__ unsigned pk2(float lo, float hi) { const cvt_f2 v = {lo, hi}; const cvt_b2 r = __builtin_convertvector(v, cvt_b2); return __builtin_bit_cast(unsigned, r); }
; #define MFMA16(a, b, c) __builtin_amdgcn_mfma_f32_16x16x32_bf16((a), (b), (c), 0, 0, 0)
; __device__ __forceinline__ void attn_phase(Frame& F, bf16* OZ) {
;     ...
;                     for (int e = 0; e < 4; ++e) { const int s = 16 * sb + 4 * g4 + e; const float z = sc[sb][e]; const bool vis = (s < nvalid) && (spos0 + s < tpos);
;                         const float sp = fmaxf(z, 0.f) + __logf(1.0f + __expf(-fabsf(z)));
;                         lk[sb][e] = vis ? -sp : 0.f; sc[sb][e] = vis ? z - sp : -1e30f; tsum[sb] += lk[sb][e]; }
;                     const float v1 = __shfl_xor(tsum[sb], 16), v2 = __shfl_xor(tsum[sb], 32), v3 = __shfl_xor(tsum[sb], 48);
;                     above[sb] = ((g4 ^ 1) > g4 ? v1 : 0.f) + ((g4 ^ 2) > g4 ? v2 : 0.f) + ((g4 ^ 3) > g4 ? v3 : 0.f);
;                     ttot[sb] = (tsum[sb] + v1) + (v2 + v3); }
;                 float after = carry;
; #pragma unroll
;     ...
; #pragma unroll
;                     for (int e = 3; e >= 0; --e) { const float w = __expf(sc[sb][e] + run); run += lk[sb][e]; sc[sb][e] = w; }
;                     after += ttot[sb]; }
;                 carry = after;
; #pragma unroll
;                 for (int kk = 0; kk < 2; ++kk) { v4u pkd; pkd.x = pk2(sc[2 * kk][0], sc[2 * kk][1]); pkd.y = pk2(sc[2 * kk][2], sc[2 * kk][3]); pkd.z = pk2(sc[2 * kk + 1][0], sc[2 * kk + 1][1]); pkd.w = pk2(sc[2 * kk + 1][2], sc[2 * kk + 1][3]);
;                     const bf16x8 pf = __builtin_bit_cast(bf16x8, pkd);
; #pragma unroll
;                     for (int dh = 0; dh < 2; ++dh) { unsigned aa[4]; bf16x8 vf[4];
; #pragma unroll
;                         for (int i = 0; i < 4; ++i) aa[i] = F.lds0 + VS + (32 * kk + 4 * g4 + q) * ST_ + (32 * (2 * dh + (i >> 1)) + 8 * p + 4 * (i & 1)) * 2;
;                         tr_read_x4(aa, 16 * ST_, vf);
; #pragma unroll
;                         for (int i = 0; i < 4; ++i) oacc[4 * dh + i] = MFMA16(vf[i], pf, oacc[4 * dh + i]); } }
;                 done = __all(carry < ATT_THR);
	v_cndmask_b32_e64 v179, 0, v69, s[8:9]
	v_add_f32_e32 v73, v73, v179
	v_pk_add_f32 v[66:67], v[66:67], v[68:69]
	v_add_f32_e32 v68, v93, v73
	v_add_f32_e32 v58, v58, v68
	v_mul_f32_e32 v58, 0x3fb8aa3b, v58
	v_exp_f32_e32 v179, v58
	v_add_f32_e32 v58, v178, v68
	v_add_f32_e32 v68, v71, v58
	v_mul_f32_e32 v68, 0x3fb8aa3b, v68
	v_cmp_gt_i32_e32 vcc, v238, v86
	v_exp_f32_e32 v178, v68
	v_add_f32_e32 v180, v70, v58
	v_cndmask_b32_e32 v159, v149, v161, vcc
	v_pk_add_f32 v[68:69], v[94:95], v[96:97]
	v_cndmask_b32_e64 v71, 0, -v165, s[18:19]
	v_cndmask_b32_e32 v70, 0, v160, vcc
	v_cmp_gt_i32_e32 vcc, v238, v75
	v_pk_add_f32 v[94:95], v[70:71], v[4:5]
	v_cndmask_b32_e64 v96, 0, -v68, s[0:1]
	v_cndmask_b32_e64 v97, 0, -v69, vcc
	v_pk_add_f32 v[94:95], v[96:97], v[94:95]
	ds_bpermute_b32 v63, v156, v95
	v_mov_b32_e32 v165, v66
	v_mov_b32_e32 v73, v67
	v_add_f32_e32 v58, v60, v180
	v_pk_add_f32 v[66:67], v[164:165], v[72:73]
	v_mul_f32_e32 v58, 0x3fb8aa3b, v58
	v_pk_add_f32 v[66:67], v[66:67], v[92:93]
	ds_bpermute_b32 v92, v154, v95
	v_exp_f32_e32 v181, v58
	v_sub_f32_e32 v58, v64, v68
	s_waitcnt lgkmcnt(1)
	v_pk_add_f32 v[72:73], v[62:63], v[94:95]
	v_sub_f32_e32 v61, v61, v69
	ds_bpermute_b32 v69, v155, v95
	v_cndmask_b32_e64 v64, v149, v58, s[0:1]
	ds_bpermute_b32 v60, v156, v72
	ds_bpermute_b32 v58, v154, v72
	v_add_f32_e32 v5, v66, v67
	ds_bpermute_b32 v66, v155, v72
	v_cndmask_b32_e32 v93, v149, v61, vcc
	v_cndmask_b32_e64 v61, 0, v63, s[4:5]
	s_waitcnt lgkmcnt(4)
	v_cndmask_b32_e64 v63, 0, v92, s[6:7]
	v_add_f32_e32 v61, v61, v63
	s_waitcnt lgkmcnt(3)
	v_cndmask_b32_e64 v63, 0, v69, s[8:9]
	s_waitcnt lgkmcnt(2)
	v_cndmask_b32_e64 v68, 0, v60, s[4:5]
	s_waitcnt lgkmcnt(1)
	v_cndmask_b32_e64 v70, 0, v58, s[6:7]
	v_add_f32_e32 v63, v61, v63
	v_add_f32_e32 v61, v92, v69
	v_add_f32_e32 v68, v68, v70
	s_waitcnt lgkmcnt(0)
	v_cndmask_b32_e64 v70, 0, v66, s[8:9]
	v_pk_add_f32 v[60:61], v[72:73], v[60:61]
	v_pk_add_f32 v[58:59], v[58:59], v[66:67]
	v_add_f32_e32 v68, v68, v70
	v_pk_add_f32 v[154:155], v[60:61], v[58:59]
	v_add_f32_e32 v63, v63, v59
	v_add_f32_e32 v58, v68, v155
	v_cndmask_b32_e64 v70, v149, v168, s[18:19]
	v_add_f32_e32 v66, v93, v63
	v_add_f32_e32 v63, v97, v63
	v_add_f32_e32 v59, v65, v58
	v_add_f32_e32 v58, v62, v58
	v_add_f32_e32 v67, v70, v63
	v_add_f32_e32 v63, v71, v63
	v_add_f32_e32 v60, v64, v58
	v_add_f32_e32 v58, v96, v58
	v_add_f32_e32 v69, v167, v63
	v_add_f32_e32 v63, v166, v63
	v_add_f32_e32 v4, v4, v58
	v_add_f32_e32 v63, v163, v63
	v_add_f32_e32 v61, v157, v58
	v_add_f32_e32 v4, v159, v4
	v_mul_f32_e32 v66, 0x3fb8aa3b, v66
	v_mul_f32_e32 v67, 0x3fb8aa3b, v67
	v_mul_f32_e32 v69, 0x3fb8aa3b, v69
	v_mul_f32_e32 v63, 0x3fb8aa3b, v63
	v_mul_f32_e32 v59, 0x3fb8aa3b, v59
	v_mul_f32_e32 v60, 0x3fb8aa3b, v60
	v_mul_f32_e32 v61, 0x3fb8aa3b, v61
	v_mul_f32_e32 v4, 0x3fb8aa3b, v4
	v_exp_f32_e32 v66, v66
	v_exp_f32_e32 v69, v69
	v_exp_f32_e32 v59, v59
	v_exp_f32_e32 v61, v61
	v_exp_f32_e32 v4, v4
	v_exp_f32_e32 v60, v60
	v_exp_f32_e32 v62, v63
	v_exp_f32_e32 v63, v67
	v_cvt_pk_bf16_f32 v58, v4, v61
	v_cvt_pk_bf16_f32 v59, v60, v59
	v_cvt_pk_bf16_f32 v60, v62, v69
	v_cvt_pk_bf16_f32 v61, v63, v66
	ds_read_b64_tr_b16 v[206:207], v110
	ds_read_b64_tr_b16 v[208:209], v114
	ds_read_b64_tr_b16 v[210:211], v111
	ds_read_b64_tr_b16 v[212:213], v115
	ds_read_b64_tr_b16 v[214:215], v112
	ds_read_b64_tr_b16 v[216:217], v116
	ds_read_b64_tr_b16 v[218:219], v113
	ds_read_b64_tr_b16 v[220:221], v117
	ds_read_b64_tr_b16 v[222:223], v118
	ds_read_b64_tr_b16 v[224:225], v122
	ds_read_b64_tr_b16 v[226:227], v119
	ds_read_b64_tr_b16 v[228:229], v123
	ds_read_b64_tr_b16 v[230:231], v120
	ds_read_b64_tr_b16 v[232:233], v124
	ds_read_b64_tr_b16 v[234:235], v121
	s_waitcnt lgkmcnt(7)
	ds_read_b64_tr_b16 v[236:237], v125
	s_nop 0
	v_add_f32_e32 v156, v177, v180
	v_add_f32_e32 v4, v176, v156
	v_mfma_f32_16x16x32_bf16 v[54:57], v[206:209], v[58:61], v[54:57]
	v_add_f32_e32 v92, v175, v5
	v_add_f32_e32 v5, v174, v5
	v_mul_f32_e32 v4, 0x3fb8aa3b, v4
	v_mfma_f32_16x16x32_bf16 v[50:53], v[210:213], v[58:61], v[50:53]
	v_mul_f32_e32 v70, 0x3fb8aa3b, v92
	v_exp_f32_e32 v96, v70
	v_exp_f32_e32 v4, v4
	v_mfma_f32_16x16x32_bf16 v[46:49], v[214:217], v[58:61], v[46:49]
	v_add_f32_e32 v66, v173, v5
	v_mul_f32_e32 v97, 0x3fb8aa3b, v66
	v_add_f32_e32 v5, v172, v5
	v_mfma_f32_16x16x32_bf16 v[42:45], v[218:221], v[58:61], v[42:45]
	ds_read_b64_tr_b16 v[206:207], v126
	ds_read_b64_tr_b16 v[208:209], v130
	ds_read_b64_tr_b16 v[210:211], v127
	ds_read_b64_tr_b16 v[212:213], v131
	ds_read_b64_tr_b16 v[214:215], v128
	ds_read_b64_tr_b16 v[216:217], v132
	ds_read_b64_tr_b16 v[218:219], v129
	s_waitcnt lgkmcnt(7)
	ds_read_b64_tr_b16 v[220:221], v133
	s_nop 0
	s_nop 0
	v_mfma_f32_16x16x32_bf16 v[38:41], v[222:225], v[58:61], v[38:41]
	v_add_f32_e32 v92, v171, v5
	v_add_f32_e32 v5, v170, v5
	v_add_f32_e32 v5, v169, v5
	v_mul_f32_e32 v92, 0x3fb8aa3b, v92
	v_mul_f32_e32 v5, 0x3fb8aa3b, v5
	v_exp_f32_e32 v92, v92
	v_mfma_f32_16x16x32_bf16 v[30:33], v[230:233], v[58:61], v[30:33]
	v_exp_f32_e32 v5, v5
	v_exp_f32_e32 v66, v97
	v_mfma_f32_16x16x32_bf16 v[34:37], v[226:229], v[58:61], v[34:37]
	v_mfma_f32_16x16x32_bf16 v[26:29], v[234:237], v[58:61], v[26:29]
	v_cvt_pk_bf16_f32 v58, v5, v92
	v_cvt_pk_bf16_f32 v59, v66, v96
	v_cvt_pk_bf16_f32 v60, v4, v181
	v_cvt_pk_bf16_f32 v61, v178, v179
	ds_read_b64_tr_b16 v[222:223], v134
	ds_read_b64_tr_b16 v[224:225], v138
	ds_read_b64_tr_b16 v[226:227], v135
	ds_read_b64_tr_b16 v[228:229], v139
	ds_read_b64_tr_b16 v[230:231], v136
	ds_read_b64_tr_b16 v[232:233], v140
	ds_read_b64_tr_b16 v[234:235], v137
	s_waitcnt lgkmcnt(7)
	ds_read_b64_tr_b16 v[236:237], v141
	s_nop 0
	s_nop 1
	v_mfma_f32_16x16x32_bf16 v[54:57], v[206:209], v[58:61], v[54:57]
	v_mfma_f32_16x16x32_bf16 v[50:53], v[210:213], v[58:61], v[50:53]
	v_mfma_f32_16x16x32_bf16 v[46:49], v[214:217], v[58:61], v[46:49]
	v_mfma_f32_16x16x32_bf16 v[42:45], v[218:221], v[58:61], v[42:45]
	s_waitcnt lgkmcnt(0)
	s_nop 0
	s_nop 0
	v_mfma_f32_16x16x32_bf16 v[38:41], v[222:225], v[58:61], v[38:41]
	v_add_f32_e32 v93, v154, v155
	v_cmp_gt_f32_e32 vcc, s55, v93
	s_cmp_eq_u64 vcc, exec
	v_mfma_f32_16x16x32_bf16 v[34:37], v[226:229], v[58:61], v[34:37]
	s_cselect_b64 s[0:1], -1, 0
	s_mov_b64 s[64:65], s[0:1]
	v_mfma_f32_16x16x32_bf16 v[30:33], v[230:233], v[58:61], v[30:33]
	v_mfma_f32_16x16x32_bf16 v[26:29], v[234:237], v[58:61], v[26:29]
	s_and_saveexec_b64 s[18:19], s[10:11]
	s_cbranch_execz .LBB0_1905
	s_branch .LBB0_1913
